# static s_setprio 1 for waves 4-7 through the two attention phases (dilated, SB/MoBA)
# speedup vs baseline: 1.0036x; 1.0036x over previous
; template <int MODE> ...
;     ...
;     const int tid = tid_, lane = tid & 63, wid = __builtin_amdgcn_readfirstlane(tid >> 6), c15 = lane & 15, g = lane >> 4;
;     const int qw0 = q0 + 32 * wid;
;     const bool hiw = wid >= 4;
.LBB0_162:
	v_readfirstlane_b32 s2, v168
	s_lshr_b32 s2, s2, 6
	s_cmp_lt_u32 s2, 4
	s_cbranch_scc1 .Lprio_skip_0
	s_setprio 1

; __device__ __forceinline__ void xcd_barrier(const XcdBarrier& b) {
;     asm volatile("s_waitcnt vmcnt(0)" ::: "memory");
;     __syncthreads();
;     if (threadIdx.x == 0) {
;         unsigned* bar = b.bar;
;         __builtin_amdgcn_s_waitcnt(0);
;         unsigned nloc = b.st[0], nx = b.st[1];
;         if (nloc == 0u) { xcd_barrier_complete(bar, b.x, nloc, nx); b.st[0] = nloc; b.st[1] = nx; }
.LBB0_227:
	s_cmp_gt_i32 s31, 3
	s_cselect_b64 s[0:1], -1, 0
	s_and_b64 s[2:3], s[40:41], s[0:1]
	s_andn2_b64 vcc, exec, s[2:3]
	s_cbranch_vccnz .LBB0_277
	s_setprio 0
	s_waitcnt vmcnt(0)
	v_cmp_eq_u32_e32 vcc, 0, v168
	s_waitcnt vmcnt(0)
	s_barrier
	s_and_saveexec_b64 s[2:3], vcc
	s_cbranch_execz .LBB0_276
	s_add_i32 s4, 0, 0x23fc0
	v_mov_b32_e32 v0, s4
	s_waitcnt vmcnt(0) expcnt(0) lgkmcnt(0)
	ds_read_b32 v2, v0
	s_add_i32 s4, 0, 0x23fc4
	v_mov_b32_e32 v0, s4
	ds_read_b32 v0, v0
	s_waitcnt lgkmcnt(1)
	v_cmp_ne_u32_e32 vcc, 0, v2
	s_cbranch_vccnz .LBB0_244
	v_readlane_b32 s4, v236, 0
	v_readlane_b32 s5, v236, 1
	s_load_dwordx2 s[8:9], s[4:5], 0x4
	s_add_u32 s4, s28, 0x1000
	s_addc_u32 s5, s29, 0
	s_add_u32 s6, s28, 0x1100
	s_addc_u32 s7, s29, 0
	s_waitcnt lgkmcnt(0)
	s_mul_i32 s18, s8, s63
	s_add_u32 s8, s28, 0x1200
	s_mul_i32 s18, s18, s9
	s_addc_u32 s9, s29, 0
	s_add_u32 s10, s28, 0x1300
	s_addc_u32 s11, s29, 0
	s_mov_b32 s19, 1
	v_mov_b32_e32 v16, 0
	s_branch .LBB0_232

; __device__ __forceinline__ void xcd_barrier(const XcdBarrier& b) {
;     asm volatile("s_waitcnt vmcnt(0)" ::: "memory");
;     __syncthreads();
;     if (threadIdx.x == 0) {
;         unsigned* bar = b.bar;
;         __builtin_amdgcn_s_waitcnt(0);
;         unsigned nloc = b.st[0], nx = b.st[1];
;         if (nloc == 0u) { xcd_barrier_complete(bar, b.x, nloc, nx); b.st[0] = nloc; b.st[1] = nx; }
.LBB0_960:
	s_cmp_gt_i32 s31, 11
	s_cselect_b64 s[0:1], -1, 0
	s_and_b64 s[2:3], s[2:3], s[0:1]
	s_andn2_b64 vcc, exec, s[2:3]
	s_cbranch_vccnz .LBB0_1010
	s_setprio 0
	s_waitcnt vmcnt(0)
	v_cmp_eq_u32_e32 vcc, 0, v168
	s_waitcnt vmcnt(0) lgkmcnt(0)
	s_barrier
	s_and_saveexec_b64 s[2:3], vcc
	s_cbranch_execz .LBB0_1009
	s_add_i32 s4, 0, 0x23fc0
	v_mov_b32_e32 v0, s4
	s_waitcnt vmcnt(0) expcnt(0) lgkmcnt(0)
	ds_read_b32 v2, v0
	s_add_i32 s4, 0, 0x23fc4
	v_mov_b32_e32 v0, s4
	ds_read_b32 v0, v0
	s_waitcnt lgkmcnt(1)
	v_cmp_ne_u32_e32 vcc, 0, v2
	s_cbranch_vccnz .LBB0_977
	v_readlane_b32 s4, v236, 0
	v_readlane_b32 s5, v236, 1
	s_load_dwordx2 s[8:9], s[4:5], 0x4
	s_add_u32 s4, s28, 0x1000
	s_addc_u32 s5, s29, 0
	s_add_u32 s6, s28, 0x1100
	s_addc_u32 s7, s29, 0
	s_waitcnt lgkmcnt(0)
	s_mul_i32 s18, s8, s63
	s_add_u32 s8, s28, 0x1200
	s_mul_i32 s18, s18, s9
	s_addc_u32 s9, s29, 0
	s_add_u32 s10, s28, 0x1300
	s_addc_u32 s11, s29, 0
	s_mov_b32 s19, 1
	v_mov_b32_e32 v16, 0
	s_branch .LBB0_965
